# P10 token prologue/epilogue loads batched, sweep loops kept at the baseline code alignment
# speedup vs baseline: 1.0013x; 1.0013x over previous
.LBB0_1698:
	s_or_b64 exec, exec, s[10:11]
	ds_read_u16 v0, v95 offset:512
	s_waitcnt lgkmcnt(1)
	ds_read_u16 v1, v95 offset:516
	ds_read_u16 v8, v95 offset:520
	ds_read_u16 v9, v95 offset:524
	s_add_i32 s34, s34, 8
	s_waitcnt lgkmcnt(3)
	v_and_b32_e32 v0, 0x3fff, v0
	s_waitcnt lgkmcnt(2)
	v_and_b32_e32 v2, 0x3fff, v1
	v_lshlrev_b32_sdwa v68, v231, v0 dst_sel:DWORD dst_unused:UNUSED_PAD src0_sel:DWORD src1_sel:WORD_0
	v_lshl_add_u64 v[0:1], v[76:77], 0, v[68:69]
	v_lshlrev_b32_sdwa v68, v231, v2 dst_sel:DWORD dst_unused:UNUSED_PAD src0_sel:DWORD src1_sel:WORD_0
	v_lshl_add_u64 v[2:3], v[76:77], 0, v[68:69]
	global_load_dwordx4 v[20:23], v[0:1], off
	global_load_dwordx4 v[4:7], v[2:3], off
	s_waitcnt lgkmcnt(1)
	v_and_b32_e32 v0, 0x3fff, v8
	v_lshlrev_b32_sdwa v68, v231, v0 dst_sel:DWORD dst_unused:UNUSED_PAD src0_sel:DWORD src1_sel:WORD_0
	s_waitcnt lgkmcnt(0)
	v_and_b32_e32 v2, 0x3fff, v9
	v_lshl_add_u64 v[0:1], v[76:77], 0, v[68:69]
	v_lshlrev_b32_sdwa v68, v231, v2 dst_sel:DWORD dst_unused:UNUSED_PAD src0_sel:DWORD src1_sel:WORD_0
	v_lshl_add_u64 v[2:3], v[76:77], 0, v[68:69]
	global_load_dwordx4 v[8:11], v[0:1], off
	s_nop 0
	global_load_dwordx4 v[0:3], v[2:3], off
	v_add_u32_e32 v95, 16, v95
	s_cmpk_gt_u32 s34, 0x6f
	v_add_u32_e32 v94, 32, v94
	s_cbranch_scc1 .LBB0_1705
	s_branch .Lpin_12
	.p2align 8
	s_nop 0
	s_nop 0
	s_nop 0
	s_nop 0
	s_nop 0
	s_nop 0
	s_nop 0
	s_nop 0
	s_nop 0
	s_nop 0
	s_nop 0
	s_nop 0
	s_nop 0
	s_nop 0
	s_nop 0
	s_nop 0
	s_nop 0
	s_nop 0
	s_nop 0
	s_nop 0
	s_nop 0
	s_nop 0
	s_nop 0
	s_nop 0
	s_nop 0
	s_nop 0
	s_nop 0
	s_nop 0
	s_nop 0
	s_nop 0
	s_nop 0
.Lpin_12:
.LBB0_1699:
	v_mov_b32_e32 v68, 0
	s_waitcnt vmcnt(11) lgkmcnt(14)
	v_dot4c_i32_i8_e32 v68, v109, v44
	v_mov_b32_e32 v44, 0
	s_waitcnt vmcnt(10)
	v_dot4c_i32_i8_e32 v44, v109, v36
	v_dot4c_i32_i8_e32 v44, v108, v37
	v_mov_b32_e32 v36, 0
	v_mov_b32_e32 v37, 0
	v_dot4c_i32_i8_e32 v68, v108, v45
	s_waitcnt vmcnt(9)
	v_dot4c_i32_i8_e32 v36, v109, v40
	s_waitcnt vmcnt(8)
	v_dot4c_i32_i8_e32 v37, v109, v32
	v_dot4c_i32_i8_e32 v68, v107, v46
	v_dot4c_i32_i8_e32 v44, v107, v38
	v_dot4c_i32_i8_e32 v36, v108, v41
	v_dot4c_i32_i8_e32 v37, v108, v33
	v_dot4c_i32_i8_e32 v68, v106, v47
	v_dot4c_i32_i8_e32 v44, v106, v39
	v_dot4c_i32_i8_e32 v36, v107, v42
	v_dot4c_i32_i8_e32 v37, v107, v34
	v_dot4c_i32_i8_e32 v36, v106, v43
	v_dot4c_i32_i8_e32 v37, v106, v35
	v_cndmask_b32_e64 v32, v44, v68, s[0:1]
	v_cndmask_b32_e64 v33, v68, v44, s[0:1]
	s_nop 0
	v_cndmask_b32_e64 v34, v36, v37, s[0:1]
	v_add_u32_dpp v32, v33, v32 quad_perm:[1,0,3,2] row_mask:0xf bank_mask:0xf bound_ctrl:1
	v_cndmask_b32_e64 v33, v37, v36, s[0:1]
	s_nop 1
	v_add_u32_dpp v33, v34, v33 quad_perm:[1,0,3,2] row_mask:0xf bank_mask:0xf bound_ctrl:1
	v_cndmask_b32_e64 v34, v33, v32, s[2:3]
	v_cndmask_b32_e64 v32, v32, v33, s[2:3]
	s_nop 1
	v_add_u32_dpp v32, v32, v34 quad_perm:[2,3,0,1] row_mask:0xf bank_mask:0xf bound_ctrl:1
	s_nop 1
	v_add_u32_dpp v32, v32, v32 row_ror:4 row_mask:0xf bank_mask:0xf bound_ctrl:1
	s_nop 1
	v_add_u32_dpp v32, v32, v32 row_ror:8 row_mask:0xf bank_mask:0xf bound_ctrl:1
	ds_bpermute_b32 v33, v215, v32
	s_and_saveexec_b64 s[10:11], s[4:5]
	s_cbranch_execz .LBB0_1701
	s_waitcnt lgkmcnt(0)
	v_add_u32_e32 v32, v32, v33
	ds_write_b32 v94, v32
